# P8 k-loop: 4 super-phases (two MFMA blocks between barriers), second DMA pair issued between the blocks, LDS reads pipelined
# baseline (speedup 1.0000x reference)
.Lp8_nostage:
	v_add_u32_e32 v168, 0x18000, v236
	v_add_u32_e32 v169, 0x1c000, v236
	ds_read_b128 v[130:133], v240
	ds_read_b128 v[134:137], v240 offset:1024
	ds_read_b128 v[138:141], v240 offset:2048
	ds_read_b128 v[142:145], v240 offset:3072
	ds_read_b128 v[146:149], v241
	ds_read_b128 v[150:153], v241 offset:1024
	ds_read_b128 v[154:157], v241 offset:2048
	ds_read_b128 v[158:161], v241 offset:3072
	ds_read_b128 v[176:179], v241 offset:4096
	ds_read_b128 v[180:183], v241 offset:5120
	ds_read_b128 v[184:187], v241 offset:6144
	ds_read_b128 v[188:191], v241 offset:7168
	s_waitcnt lgkmcnt(0)
	s_barrier
	s_add_u32 s50, s48, 0xfff80080
	s_addc_u32 s51, s49, -1
	s_cmp_eq_u32 s80, s87
	s_cselect_b32 s53, s41, s51
	s_cselect_b32 s52, s47, s50
	s_cselect_b32 s51, s39, s75
	s_cselect_b32 s50, s73, s74
	s_add_i32 m0, s21, 0xc000
	s_nop 0
	global_load_lds_dwordx4 v166, s[48:49]
	s_add_i32 m0, s21, 0xe000
	s_nop 0
	global_load_lds_dwordx4 v170, s[48:49]
	s_waitcnt vmcnt(8)
	s_barrier
	s_waitcnt lgkmcnt(0)
	s_setprio 1
	v_mfma_f32_16x16x32_bf16 v[126:129], v[130:133], v[146:149], 0
	ds_read_b128 v[192:195], v242
	v_mfma_f32_16x16x32_bf16 v[122:125], v[138:141], v[146:149], 0
	v_mfma_f32_16x16x32_bf16 v[118:121], v[130:133], v[154:157], 0
	ds_read_b128 v[196:199], v242 offset:1024
	v_mfma_f32_16x16x32_bf16 v[114:117], v[138:141], v[154:157], 0
	v_mfma_f32_16x16x32_bf16 v[106:109], v[130:133], v[176:179], 0
	ds_read_b128 v[200:203], v242 offset:2048
	v_mfma_f32_16x16x32_bf16 v[98:101], v[138:141], v[176:179], 0
	v_mfma_f32_16x16x32_bf16 v[90:93], v[130:133], v[184:187], 0
	ds_read_b128 v[204:207], v242 offset:3072
	v_mfma_f32_16x16x32_bf16 v[82:85], v[138:141], v[184:187], 0
	v_mfma_f32_16x16x32_bf16 v[126:129], v[134:137], v[150:153], v[126:129]
	v_mfma_f32_16x16x32_bf16 v[122:125], v[142:145], v[150:153], v[122:125]
	v_mfma_f32_16x16x32_bf16 v[118:121], v[134:137], v[158:161], v[118:121]
	v_mfma_f32_16x16x32_bf16 v[114:117], v[142:145], v[158:161], v[114:117]
	v_mfma_f32_16x16x32_bf16 v[106:109], v[134:137], v[180:183], v[106:109]
	v_mfma_f32_16x16x32_bf16 v[98:101], v[142:145], v[180:183], v[98:101]
	v_mfma_f32_16x16x32_bf16 v[90:93], v[134:137], v[188:191], v[90:93]
	v_mfma_f32_16x16x32_bf16 v[82:85], v[142:145], v[188:191], v[82:85]
	s_waitcnt lgkmcnt(0)
	s_add_i32 s81, s68, s56
	s_add_u32 s96, s50, 0x80
	s_addc_u32 s97, s51, 0
	s_mov_b32 m0, s81
	s_nop 0
	global_load_lds_dwordx4 v162, s[50:51]
	s_add_i32 m0, s81, 0x2000
	s_nop 0
	global_load_lds_dwordx4 v164, s[50:51]
	v_mfma_f32_16x16x32_bf16 v[110:113], v[192:195], v[146:149], 0
	ds_read_b128 v[208:211], v241 offset:16384
	v_mfma_f32_16x16x32_bf16 v[102:105], v[200:203], v[146:149], 0
	v_mfma_f32_16x16x32_bf16 v[94:97], v[192:195], v[154:157], 0
	ds_read_b128 v[212:215], v241 offset:17408
	v_mfma_f32_16x16x32_bf16 v[86:89], v[200:203], v[154:157], 0
	v_mfma_f32_16x16x32_bf16 v[78:81], v[192:195], v[176:179], 0
	ds_read_b128 v[216:219], v241 offset:18432
	v_mfma_f32_16x16x32_bf16 v[74:77], v[200:203], v[176:179], 0
	v_mfma_f32_16x16x32_bf16 v[70:73], v[192:195], v[184:187], 0
	ds_read_b128 v[220:223], v241 offset:19456
	v_mfma_f32_16x16x32_bf16 v[66:69], v[200:203], v[184:187], 0
	v_mfma_f32_16x16x32_bf16 v[110:113], v[196:199], v[150:153], v[110:113]
	ds_read_b128 v[224:227], v241 offset:20480
	v_mfma_f32_16x16x32_bf16 v[102:105], v[204:207], v[150:153], v[102:105]
	v_mfma_f32_16x16x32_bf16 v[94:97], v[196:199], v[158:161], v[94:97]
	ds_read_b128 v[228:231], v241 offset:21504
	v_mfma_f32_16x16x32_bf16 v[86:89], v[204:207], v[158:161], v[86:89]
	v_mfma_f32_16x16x32_bf16 v[78:81], v[196:199], v[180:183], v[78:81]
	ds_read_b128 v[232:235], v241 offset:22528
	v_mfma_f32_16x16x32_bf16 v[74:77], v[204:207], v[180:183], v[74:77]
	v_mfma_f32_16x16x32_bf16 v[70:73], v[196:199], v[188:191], v[70:73]
	ds_read_b128 v[246:249], v241 offset:23552
	v_mfma_f32_16x16x32_bf16 v[66:69], v[204:207], v[188:191], v[66:69]
	s_waitcnt lgkmcnt(0)
	s_setprio 0
	s_barrier
	s_mov_b32 m0, s21
	s_add_u32 s94, s52, 0x80
	s_addc_u32 s95, s53, 0
	global_load_lds_dwordx4 v162, s[52:53]
	s_mov_b32 m0, s59
	s_nop 0
	global_load_lds_dwordx4 v164, s[52:53]
	s_waitcnt vmcnt(8)
	s_barrier
	s_waitcnt lgkmcnt(0)
	s_setprio 1
	v_mfma_f32_16x16x32_bf16 v[62:65], v[130:133], v[208:211], 0
	ds_read_b128 v[146:149], v241 offset:32768
	v_mfma_f32_16x16x32_bf16 v[58:61], v[138:141], v[208:211], 0
	v_mfma_f32_16x16x32_bf16 v[54:57], v[130:133], v[216:219], 0
	ds_read_b128 v[150:153], v241 offset:33792
	v_mfma_f32_16x16x32_bf16 v[50:53], v[138:141], v[216:219], 0
	v_mfma_f32_16x16x32_bf16 v[42:45], v[130:133], v[224:227], 0
	ds_read_b128 v[154:157], v241 offset:34816
	v_mfma_f32_16x16x32_bf16 v[34:37], v[138:141], v[224:227], 0
	v_mfma_f32_16x16x32_bf16 v[26:29], v[130:133], v[232:235], 0
	ds_read_b128 v[158:161], v241 offset:35840
	v_mfma_f32_16x16x32_bf16 v[18:21], v[138:141], v[232:235], 0
	v_mfma_f32_16x16x32_bf16 v[62:65], v[134:137], v[212:215], v[62:65]
	ds_read_b128 v[176:179], v241 offset:36864
	v_mfma_f32_16x16x32_bf16 v[58:61], v[142:145], v[212:215], v[58:61]
	v_mfma_f32_16x16x32_bf16 v[54:57], v[134:137], v[220:223], v[54:57]
	ds_read_b128 v[180:183], v241 offset:37888
	v_mfma_f32_16x16x32_bf16 v[50:53], v[142:145], v[220:223], v[50:53]
	v_mfma_f32_16x16x32_bf16 v[42:45], v[134:137], v[228:231], v[42:45]
	ds_read_b128 v[184:187], v241 offset:38912
	v_mfma_f32_16x16x32_bf16 v[34:37], v[142:145], v[228:231], v[34:37]
	v_mfma_f32_16x16x32_bf16 v[26:29], v[134:137], v[246:249], v[26:29]
	ds_read_b128 v[188:191], v241 offset:39936
	v_mfma_f32_16x16x32_bf16 v[18:21], v[142:145], v[246:249], v[18:21]
	s_add_u32 s82, s50, 0x80000
	s_addc_u32 s83, s51, 0
	s_add_i32 s81, s69, s56
	s_mov_b32 m0, s81
	s_nop 0
	global_load_lds_dwordx4 v162, s[82:83]
	s_add_i32 m0, s81, 0x2000
	s_nop 0
	global_load_lds_dwordx4 v164, s[82:83]
	v_mfma_f32_16x16x32_bf16 v[46:49], v[192:195], v[208:211], 0
	v_mfma_f32_16x16x32_bf16 v[38:41], v[200:203], v[208:211], 0
	v_mfma_f32_16x16x32_bf16 v[30:33], v[192:195], v[216:219], 0
	v_mfma_f32_16x16x32_bf16 v[22:25], v[200:203], v[216:219], 0
	ds_read_b128 v[130:133], v168
	v_mfma_f32_16x16x32_bf16 v[14:17], v[192:195], v[224:227], 0
	v_mfma_f32_16x16x32_bf16 v[10:13], v[200:203], v[224:227], 0
	ds_read_b128 v[134:137], v168 offset:1024
	v_mfma_f32_16x16x32_bf16 v[6:9], v[192:195], v[232:235], 0
	v_mfma_f32_16x16x32_bf16 v[2:5], v[200:203], v[232:235], 0
	ds_read_b128 v[138:141], v168 offset:2048
	v_mfma_f32_16x16x32_bf16 v[46:49], v[196:199], v[212:215], v[46:49]
	v_mfma_f32_16x16x32_bf16 v[38:41], v[204:207], v[212:215], v[38:41]
	ds_read_b128 v[142:145], v168 offset:3072
	v_mfma_f32_16x16x32_bf16 v[30:33], v[196:199], v[220:223], v[30:33]
	v_mfma_f32_16x16x32_bf16 v[22:25], v[204:207], v[220:223], v[22:25]
	v_mfma_f32_16x16x32_bf16 v[14:17], v[196:199], v[228:231], v[14:17]
	v_mfma_f32_16x16x32_bf16 v[10:13], v[204:207], v[228:231], v[10:13]
	v_mfma_f32_16x16x32_bf16 v[6:9], v[196:199], v[246:249], v[6:9]
	v_mfma_f32_16x16x32_bf16 v[2:5], v[204:207], v[246:249], v[2:5]
	s_waitcnt lgkmcnt(0)
	s_setprio 0
	s_barrier
	s_add_i32 s81, 0, 0x18000
	s_add_u32 s52, s52, 0x80000
	s_addc_u32 s53, s53, 0
	s_mov_b32 m0, s60
	s_nop 0
	global_load_lds_dwordx4 v162, s[52:53]
	s_mov_b32 m0, s61
	s_nop 0
	global_load_lds_dwordx4 v164, s[52:53]
	s_waitcnt vmcnt(8)
	s_barrier
	s_waitcnt lgkmcnt(0)
	s_setprio 1
	v_mfma_f32_16x16x32_bf16 v[126:129], v[130:133], v[146:149], v[126:129]
	ds_read_b128 v[192:195], v169
	v_mfma_f32_16x16x32_bf16 v[122:125], v[138:141], v[146:149], v[122:125]
	v_mfma_f32_16x16x32_bf16 v[118:121], v[130:133], v[154:157], v[118:121]
	ds_read_b128 v[196:199], v169 offset:1024
	v_mfma_f32_16x16x32_bf16 v[114:117], v[138:141], v[154:157], v[114:117]
	v_mfma_f32_16x16x32_bf16 v[106:109], v[130:133], v[176:179], v[106:109]
	ds_read_b128 v[200:203], v169 offset:2048
	v_mfma_f32_16x16x32_bf16 v[98:101], v[138:141], v[176:179], v[98:101]
	v_mfma_f32_16x16x32_bf16 v[90:93], v[130:133], v[184:187], v[90:93]
	ds_read_b128 v[204:207], v169 offset:3072
	v_mfma_f32_16x16x32_bf16 v[82:85], v[138:141], v[184:187], v[82:85]
	v_mfma_f32_16x16x32_bf16 v[126:129], v[134:137], v[150:153], v[126:129]
	v_mfma_f32_16x16x32_bf16 v[122:125], v[142:145], v[150:153], v[122:125]
	v_mfma_f32_16x16x32_bf16 v[118:121], v[134:137], v[158:161], v[118:121]
	v_mfma_f32_16x16x32_bf16 v[114:117], v[142:145], v[158:161], v[114:117]
	v_mfma_f32_16x16x32_bf16 v[106:109], v[134:137], v[180:183], v[106:109]
	v_mfma_f32_16x16x32_bf16 v[98:101], v[142:145], v[180:183], v[98:101]
	v_mfma_f32_16x16x32_bf16 v[90:93], v[134:137], v[188:191], v[90:93]
	v_mfma_f32_16x16x32_bf16 v[82:85], v[142:145], v[188:191], v[82:85]
	s_waitcnt lgkmcnt(0)
	s_add_i32 s52, 0, 0x1c000
	s_add_i32 s53, s81, s56
	s_mov_b32 m0, s53
	s_nop 0
	global_load_lds_dwordx4 v162, s[96:97]
	s_add_i32 m0, s53, 0x2000
	s_nop 0
	global_load_lds_dwordx4 v164, s[96:97]
	v_mfma_f32_16x16x32_bf16 v[110:113], v[192:195], v[146:149], v[110:113]
	ds_read_b128 v[208:211], v241 offset:49152
	v_mfma_f32_16x16x32_bf16 v[102:105], v[200:203], v[146:149], v[102:105]
	v_mfma_f32_16x16x32_bf16 v[94:97], v[192:195], v[154:157], v[94:97]
	ds_read_b128 v[212:215], v241 offset:50176
	v_mfma_f32_16x16x32_bf16 v[86:89], v[200:203], v[154:157], v[86:89]
	v_mfma_f32_16x16x32_bf16 v[78:81], v[192:195], v[176:179], v[78:81]
	ds_read_b128 v[216:219], v241 offset:51200
	v_mfma_f32_16x16x32_bf16 v[74:77], v[200:203], v[176:179], v[74:77]
	v_mfma_f32_16x16x32_bf16 v[70:73], v[192:195], v[184:187], v[70:73]
	ds_read_b128 v[220:223], v241 offset:52224
	v_mfma_f32_16x16x32_bf16 v[66:69], v[200:203], v[184:187], v[66:69]
	v_mfma_f32_16x16x32_bf16 v[110:113], v[196:199], v[150:153], v[110:113]
	ds_read_b128 v[224:227], v241 offset:53248
	v_mfma_f32_16x16x32_bf16 v[102:105], v[204:207], v[150:153], v[102:105]
	v_mfma_f32_16x16x32_bf16 v[94:97], v[196:199], v[158:161], v[94:97]
	ds_read_b128 v[228:231], v241 offset:54272
	v_mfma_f32_16x16x32_bf16 v[86:89], v[204:207], v[158:161], v[86:89]
	v_mfma_f32_16x16x32_bf16 v[78:81], v[196:199], v[180:183], v[78:81]
	ds_read_b128 v[232:235], v241 offset:55296
	v_mfma_f32_16x16x32_bf16 v[74:77], v[204:207], v[180:183], v[74:77]
	v_mfma_f32_16x16x32_bf16 v[70:73], v[196:199], v[188:191], v[70:73]
	ds_read_b128 v[246:249], v241 offset:56320
	v_mfma_f32_16x16x32_bf16 v[66:69], v[204:207], v[188:191], v[66:69]
	s_waitcnt lgkmcnt(0)
	s_setprio 0
	s_barrier
	s_mov_b32 m0, s64
	s_nop 0
	global_load_lds_dwordx4 v162, s[94:95]
	s_mov_b32 m0, s65
	s_nop 0
	global_load_lds_dwordx4 v164, s[94:95]
	s_waitcnt vmcnt(8)
	s_barrier
	s_waitcnt lgkmcnt(0)
	s_setprio 1
	v_mfma_f32_16x16x32_bf16 v[62:65], v[130:133], v[208:211], v[62:65]
	ds_read_b128 v[146:149], v241
	v_mfma_f32_16x16x32_bf16 v[58:61], v[138:141], v[208:211], v[58:61]
	v_mfma_f32_16x16x32_bf16 v[54:57], v[130:133], v[216:219], v[54:57]
	ds_read_b128 v[150:153], v241 offset:1024
	v_mfma_f32_16x16x32_bf16 v[50:53], v[138:141], v[216:219], v[50:53]
	v_mfma_f32_16x16x32_bf16 v[42:45], v[130:133], v[224:227], v[42:45]
	ds_read_b128 v[154:157], v241 offset:2048
	v_mfma_f32_16x16x32_bf16 v[34:37], v[138:141], v[224:227], v[34:37]
	v_mfma_f32_16x16x32_bf16 v[26:29], v[130:133], v[232:235], v[26:29]
	ds_read_b128 v[158:161], v241 offset:3072
	v_mfma_f32_16x16x32_bf16 v[18:21], v[138:141], v[232:235], v[18:21]
	v_mfma_f32_16x16x32_bf16 v[62:65], v[134:137], v[212:215], v[62:65]
	ds_read_b128 v[176:179], v241 offset:4096
	v_mfma_f32_16x16x32_bf16 v[58:61], v[142:145], v[212:215], v[58:61]
	v_mfma_f32_16x16x32_bf16 v[54:57], v[134:137], v[220:223], v[54:57]
	ds_read_b128 v[180:183], v241 offset:5120
	v_mfma_f32_16x16x32_bf16 v[50:53], v[142:145], v[220:223], v[50:53]
	v_mfma_f32_16x16x32_bf16 v[42:45], v[134:137], v[228:231], v[42:45]
	ds_read_b128 v[184:187], v241 offset:6144
	v_mfma_f32_16x16x32_bf16 v[34:37], v[142:145], v[228:231], v[34:37]
	v_mfma_f32_16x16x32_bf16 v[26:29], v[134:137], v[246:249], v[26:29]
	ds_read_b128 v[188:191], v241 offset:7168
	v_mfma_f32_16x16x32_bf16 v[18:21], v[142:145], v[246:249], v[18:21]
	s_add_u32 s50, s50, 0x80080
	s_addc_u32 s51, s51, 0
	s_add_i32 s52, s52, s56
	s_mov_b32 m0, s52
	s_nop 0
	global_load_lds_dwordx4 v162, s[50:51]
	s_add_i32 m0, s52, 0x2000
	s_nop 0
	global_load_lds_dwordx4 v164, s[50:51]
	v_mfma_f32_16x16x32_bf16 v[46:49], v[192:195], v[208:211], v[46:49]
	v_mfma_f32_16x16x32_bf16 v[38:41], v[200:203], v[208:211], v[38:41]
	v_mfma_f32_16x16x32_bf16 v[30:33], v[192:195], v[216:219], v[30:33]
	v_mfma_f32_16x16x32_bf16 v[22:25], v[200:203], v[216:219], v[22:25]
	ds_read_b128 v[130:133], v240
	v_mfma_f32_16x16x32_bf16 v[14:17], v[192:195], v[224:227], v[14:17]
	v_mfma_f32_16x16x32_bf16 v[10:13], v[200:203], v[224:227], v[10:13]
	ds_read_b128 v[134:137], v240 offset:1024
	v_mfma_f32_16x16x32_bf16 v[6:9], v[192:195], v[232:235], v[6:9]
	v_mfma_f32_16x16x32_bf16 v[2:5], v[200:203], v[232:235], v[2:5]
	ds_read_b128 v[138:141], v240 offset:2048
	v_mfma_f32_16x16x32_bf16 v[46:49], v[196:199], v[212:215], v[46:49]
	v_mfma_f32_16x16x32_bf16 v[38:41], v[204:207], v[212:215], v[38:41]
	ds_read_b128 v[142:145], v240 offset:3072
	v_mfma_f32_16x16x32_bf16 v[30:33], v[196:199], v[220:223], v[30:33]
	v_mfma_f32_16x16x32_bf16 v[22:25], v[204:207], v[220:223], v[22:25]
	v_mfma_f32_16x16x32_bf16 v[14:17], v[196:199], v[228:231], v[14:17]
	v_mfma_f32_16x16x32_bf16 v[10:13], v[204:207], v[228:231], v[10:13]
	v_mfma_f32_16x16x32_bf16 v[6:9], v[196:199], v[246:249], v[6:9]
	v_mfma_f32_16x16x32_bf16 v[2:5], v[204:207], v[246:249], v[2:5]
	s_waitcnt lgkmcnt(0)
	s_setprio 0
	s_add_i32 s80, s80, 2
	s_add_u32 s48, s48, 0x100
	s_addc_u32 s49, s49, 0
	s_add_u32 s74, s74, 0x100
	s_addc_u32 s75, s75, 0
	s_cmp_gt_u32 s80, s87
	s_barrier
	s_cbranch_scc0 .LBB0_1098
	s_branch .Lp8_loop_exit
.LBB0_1098:
	s_add_u32 s50, s48, 0xfff80080
	s_addc_u32 s51, s49, -1
	s_cmp_eq_u32 s80, s87
	s_cselect_b32 s53, s41, s51
	s_cselect_b32 s52, s47, s50
	s_cselect_b32 s51, s39, s75
	s_cselect_b32 s50, s73, s74
	s_add_i32 m0, s21, 0xc000
	s_nop 0
	global_load_lds_dwordx4 v166, s[48:49]
	s_add_i32 m0, s21, 0xe000
	s_nop 0
	global_load_lds_dwordx4 v170, s[48:49]
	s_waitcnt vmcnt(8)
	s_barrier
	s_waitcnt lgkmcnt(0)
	s_setprio 1
	v_mfma_f32_16x16x32_bf16 v[126:129], v[130:133], v[146:149], v[126:129]
	ds_read_b128 v[192:195], v242
	v_mfma_f32_16x16x32_bf16 v[122:125], v[138:141], v[146:149], v[122:125]
	v_mfma_f32_16x16x32_bf16 v[118:121], v[130:133], v[154:157], v[118:121]
	ds_read_b128 v[196:199], v242 offset:1024
	v_mfma_f32_16x16x32_bf16 v[114:117], v[138:141], v[154:157], v[114:117]
	v_mfma_f32_16x16x32_bf16 v[106:109], v[130:133], v[176:179], v[106:109]
	ds_read_b128 v[200:203], v242 offset:2048
	v_mfma_f32_16x16x32_bf16 v[98:101], v[138:141], v[176:179], v[98:101]
	v_mfma_f32_16x16x32_bf16 v[90:93], v[130:133], v[184:187], v[90:93]
	ds_read_b128 v[204:207], v242 offset:3072
	v_mfma_f32_16x16x32_bf16 v[82:85], v[138:141], v[184:187], v[82:85]
	v_mfma_f32_16x16x32_bf16 v[126:129], v[134:137], v[150:153], v[126:129]
	v_mfma_f32_16x16x32_bf16 v[122:125], v[142:145], v[150:153], v[122:125]
	v_mfma_f32_16x16x32_bf16 v[118:121], v[134:137], v[158:161], v[118:121]
	v_mfma_f32_16x16x32_bf16 v[114:117], v[142:145], v[158:161], v[114:117]
	v_mfma_f32_16x16x32_bf16 v[106:109], v[134:137], v[180:183], v[106:109]
	v_mfma_f32_16x16x32_bf16 v[98:101], v[142:145], v[180:183], v[98:101]
	v_mfma_f32_16x16x32_bf16 v[90:93], v[134:137], v[188:191], v[90:93]
	v_mfma_f32_16x16x32_bf16 v[82:85], v[142:145], v[188:191], v[82:85]
	s_waitcnt lgkmcnt(0)
	s_add_i32 s81, s68, s56
	s_add_u32 s96, s50, 0x80
	s_addc_u32 s97, s51, 0
	s_mov_b32 m0, s81
	s_nop 0
	global_load_lds_dwordx4 v162, s[50:51]
	s_add_i32 m0, s81, 0x2000
	s_nop 0
	global_load_lds_dwordx4 v164, s[50:51]
	v_mfma_f32_16x16x32_bf16 v[110:113], v[192:195], v[146:149], v[110:113]
	ds_read_b128 v[208:211], v241 offset:16384
	v_mfma_f32_16x16x32_bf16 v[102:105], v[200:203], v[146:149], v[102:105]
	v_mfma_f32_16x16x32_bf16 v[94:97], v[192:195], v[154:157], v[94:97]
	ds_read_b128 v[212:215], v241 offset:17408
	v_mfma_f32_16x16x32_bf16 v[86:89], v[200:203], v[154:157], v[86:89]
	v_mfma_f32_16x16x32_bf16 v[78:81], v[192:195], v[176:179], v[78:81]
	ds_read_b128 v[216:219], v241 offset:18432
	v_mfma_f32_16x16x32_bf16 v[74:77], v[200:203], v[176:179], v[74:77]
	v_mfma_f32_16x16x32_bf16 v[70:73], v[192:195], v[184:187], v[70:73]
	ds_read_b128 v[220:223], v241 offset:19456
	v_mfma_f32_16x16x32_bf16 v[66:69], v[200:203], v[184:187], v[66:69]
	v_mfma_f32_16x16x32_bf16 v[110:113], v[196:199], v[150:153], v[110:113]
	ds_read_b128 v[224:227], v241 offset:20480
	v_mfma_f32_16x16x32_bf16 v[102:105], v[204:207], v[150:153], v[102:105]
	v_mfma_f32_16x16x32_bf16 v[94:97], v[196:199], v[158:161], v[94:97]
	ds_read_b128 v[228:231], v241 offset:21504
	v_mfma_f32_16x16x32_bf16 v[86:89], v[204:207], v[158:161], v[86:89]
	v_mfma_f32_16x16x32_bf16 v[78:81], v[196:199], v[180:183], v[78:81]
	ds_read_b128 v[232:235], v241 offset:22528
	v_mfma_f32_16x16x32_bf16 v[74:77], v[204:207], v[180:183], v[74:77]
	v_mfma_f32_16x16x32_bf16 v[70:73], v[196:199], v[188:191], v[70:73]
	ds_read_b128 v[246:249], v241 offset:23552
	v_mfma_f32_16x16x32_bf16 v[66:69], v[204:207], v[188:191], v[66:69]
	s_waitcnt lgkmcnt(0)
	s_setprio 0
	s_barrier
	s_mov_b32 m0, s21
	s_add_u32 s94, s52, 0x80
	s_addc_u32 s95, s53, 0
	global_load_lds_dwordx4 v162, s[52:53]
	s_mov_b32 m0, s59
	s_nop 0
	global_load_lds_dwordx4 v164, s[52:53]
	s_waitcnt vmcnt(8)
	s_barrier
	s_waitcnt lgkmcnt(0)
	s_setprio 1
	v_mfma_f32_16x16x32_bf16 v[62:65], v[130:133], v[208:211], v[62:65]
	ds_read_b128 v[146:149], v241 offset:32768
	v_mfma_f32_16x16x32_bf16 v[58:61], v[138:141], v[208:211], v[58:61]
	v_mfma_f32_16x16x32_bf16 v[54:57], v[130:133], v[216:219], v[54:57]
	ds_read_b128 v[150:153], v241 offset:33792
	v_mfma_f32_16x16x32_bf16 v[50:53], v[138:141], v[216:219], v[50:53]
	v_mfma_f32_16x16x32_bf16 v[42:45], v[130:133], v[224:227], v[42:45]
	ds_read_b128 v[154:157], v241 offset:34816
	v_mfma_f32_16x16x32_bf16 v[34:37], v[138:141], v[224:227], v[34:37]
	v_mfma_f32_16x16x32_bf16 v[26:29], v[130:133], v[232:235], v[26:29]
	ds_read_b128 v[158:161], v241 offset:35840
	v_mfma_f32_16x16x32_bf16 v[18:21], v[138:141], v[232:235], v[18:21]
	v_mfma_f32_16x16x32_bf16 v[62:65], v[134:137], v[212:215], v[62:65]
	ds_read_b128 v[176:179], v241 offset:36864
	v_mfma_f32_16x16x32_bf16 v[58:61], v[142:145], v[212:215], v[58:61]
	v_mfma_f32_16x16x32_bf16 v[54:57], v[134:137], v[220:223], v[54:57]
	ds_read_b128 v[180:183], v241 offset:37888
	v_mfma_f32_16x16x32_bf16 v[50:53], v[142:145], v[220:223], v[50:53]
	v_mfma_f32_16x16x32_bf16 v[42:45], v[134:137], v[228:231], v[42:45]
	ds_read_b128 v[184:187], v241 offset:38912
	v_mfma_f32_16x16x32_bf16 v[34:37], v[142:145], v[228:231], v[34:37]
	v_mfma_f32_16x16x32_bf16 v[26:29], v[134:137], v[246:249], v[26:29]
	ds_read_b128 v[188:191], v241 offset:39936
	v_mfma_f32_16x16x32_bf16 v[18:21], v[142:145], v[246:249], v[18:21]
	s_add_u32 s82, s50, 0x80000
	s_addc_u32 s83, s51, 0
	s_add_i32 s81, s69, s56
	s_mov_b32 m0, s81
	s_nop 0
	global_load_lds_dwordx4 v162, s[82:83]
	s_add_i32 m0, s81, 0x2000
	s_nop 0
	global_load_lds_dwordx4 v164, s[82:83]
	v_mfma_f32_16x16x32_bf16 v[46:49], v[192:195], v[208:211], v[46:49]
	v_mfma_f32_16x16x32_bf16 v[38:41], v[200:203], v[208:211], v[38:41]
	v_mfma_f32_16x16x32_bf16 v[30:33], v[192:195], v[216:219], v[30:33]
	v_mfma_f32_16x16x32_bf16 v[22:25], v[200:203], v[216:219], v[22:25]
	ds_read_b128 v[130:133], v168
	v_mfma_f32_16x16x32_bf16 v[14:17], v[192:195], v[224:227], v[14:17]
	v_mfma_f32_16x16x32_bf16 v[10:13], v[200:203], v[224:227], v[10:13]
	ds_read_b128 v[134:137], v168 offset:1024
	v_mfma_f32_16x16x32_bf16 v[6:9], v[192:195], v[232:235], v[6:9]
	v_mfma_f32_16x16x32_bf16 v[2:5], v[200:203], v[232:235], v[2:5]
	ds_read_b128 v[138:141], v168 offset:2048
	v_mfma_f32_16x16x32_bf16 v[46:49], v[196:199], v[212:215], v[46:49]
	v_mfma_f32_16x16x32_bf16 v[38:41], v[204:207], v[212:215], v[38:41]
	ds_read_b128 v[142:145], v168 offset:3072
	v_mfma_f32_16x16x32_bf16 v[30:33], v[196:199], v[220:223], v[30:33]
	v_mfma_f32_16x16x32_bf16 v[22:25], v[204:207], v[220:223], v[22:25]
	v_mfma_f32_16x16x32_bf16 v[14:17], v[196:199], v[228:231], v[14:17]
	v_mfma_f32_16x16x32_bf16 v[10:13], v[204:207], v[228:231], v[10:13]
	v_mfma_f32_16x16x32_bf16 v[6:9], v[196:199], v[246:249], v[6:9]
	v_mfma_f32_16x16x32_bf16 v[2:5], v[204:207], v[246:249], v[2:5]
	s_waitcnt lgkmcnt(0)
	s_setprio 0
	s_barrier
	s_add_i32 s81, 0, 0x18000
	s_add_u32 s52, s52, 0x80000
	s_addc_u32 s53, s53, 0
	s_mov_b32 m0, s60
	s_nop 0
	global_load_lds_dwordx4 v162, s[52:53]
	s_mov_b32 m0, s61
	s_nop 0
	global_load_lds_dwordx4 v164, s[52:53]
	s_waitcnt vmcnt(8)
	s_barrier
	s_waitcnt lgkmcnt(0)
	s_setprio 1
	v_mfma_f32_16x16x32_bf16 v[126:129], v[130:133], v[146:149], v[126:129]
	ds_read_b128 v[192:195], v169
	v_mfma_f32_16x16x32_bf16 v[122:125], v[138:141], v[146:149], v[122:125]
	v_mfma_f32_16x16x32_bf16 v[118:121], v[130:133], v[154:157], v[118:121]
	ds_read_b128 v[196:199], v169 offset:1024
	v_mfma_f32_16x16x32_bf16 v[114:117], v[138:141], v[154:157], v[114:117]
	v_mfma_f32_16x16x32_bf16 v[106:109], v[130:133], v[176:179], v[106:109]
	ds_read_b128 v[200:203], v169 offset:2048
	v_mfma_f32_16x16x32_bf16 v[98:101], v[138:141], v[176:179], v[98:101]
	v_mfma_f32_16x16x32_bf16 v[90:93], v[130:133], v[184:187], v[90:93]
	ds_read_b128 v[204:207], v169 offset:3072
	v_mfma_f32_16x16x32_bf16 v[82:85], v[138:141], v[184:187], v[82:85]
	v_mfma_f32_16x16x32_bf16 v[126:129], v[134:137], v[150:153], v[126:129]
	v_mfma_f32_16x16x32_bf16 v[122:125], v[142:145], v[150:153], v[122:125]
	v_mfma_f32_16x16x32_bf16 v[118:121], v[134:137], v[158:161], v[118:121]
	v_mfma_f32_16x16x32_bf16 v[114:117], v[142:145], v[158:161], v[114:117]
	v_mfma_f32_16x16x32_bf16 v[106:109], v[134:137], v[180:183], v[106:109]
	v_mfma_f32_16x16x32_bf16 v[98:101], v[142:145], v[180:183], v[98:101]
	v_mfma_f32_16x16x32_bf16 v[90:93], v[134:137], v[188:191], v[90:93]
	v_mfma_f32_16x16x32_bf16 v[82:85], v[142:145], v[188:191], v[82:85]
	s_waitcnt lgkmcnt(0)
	s_add_i32 s52, 0, 0x1c000
	s_add_i32 s53, s81, s56
	s_mov_b32 m0, s53
	s_nop 0
	global_load_lds_dwordx4 v162, s[96:97]
	s_add_i32 m0, s53, 0x2000
	s_nop 0
	global_load_lds_dwordx4 v164, s[96:97]
	v_mfma_f32_16x16x32_bf16 v[110:113], v[192:195], v[146:149], v[110:113]
	ds_read_b128 v[208:211], v241 offset:49152
	v_mfma_f32_16x16x32_bf16 v[102:105], v[200:203], v[146:149], v[102:105]
	v_mfma_f32_16x16x32_bf16 v[94:97], v[192:195], v[154:157], v[94:97]
	ds_read_b128 v[212:215], v241 offset:50176
	v_mfma_f32_16x16x32_bf16 v[86:89], v[200:203], v[154:157], v[86:89]
	v_mfma_f32_16x16x32_bf16 v[78:81], v[192:195], v[176:179], v[78:81]
	ds_read_b128 v[216:219], v241 offset:51200
	v_mfma_f32_16x16x32_bf16 v[74:77], v[200:203], v[176:179], v[74:77]
	v_mfma_f32_16x16x32_bf16 v[70:73], v[192:195], v[184:187], v[70:73]
	ds_read_b128 v[220:223], v241 offset:52224
	v_mfma_f32_16x16x32_bf16 v[66:69], v[200:203], v[184:187], v[66:69]
	v_mfma_f32_16x16x32_bf16 v[110:113], v[196:199], v[150:153], v[110:113]
	ds_read_b128 v[224:227], v241 offset:53248
	v_mfma_f32_16x16x32_bf16 v[102:105], v[204:207], v[150:153], v[102:105]
	v_mfma_f32_16x16x32_bf16 v[94:97], v[196:199], v[158:161], v[94:97]
	ds_read_b128 v[228:231], v241 offset:54272
	v_mfma_f32_16x16x32_bf16 v[86:89], v[204:207], v[158:161], v[86:89]
	v_mfma_f32_16x16x32_bf16 v[78:81], v[196:199], v[180:183], v[78:81]
	ds_read_b128 v[232:235], v241 offset:55296
	v_mfma_f32_16x16x32_bf16 v[74:77], v[204:207], v[180:183], v[74:77]
	v_mfma_f32_16x16x32_bf16 v[70:73], v[196:199], v[188:191], v[70:73]
	ds_read_b128 v[246:249], v241 offset:56320
	v_mfma_f32_16x16x32_bf16 v[66:69], v[204:207], v[188:191], v[66:69]
	s_waitcnt lgkmcnt(0)
	s_setprio 0
	s_barrier
	s_mov_b32 m0, s64
	s_nop 0
	global_load_lds_dwordx4 v162, s[94:95]
	s_mov_b32 m0, s65
	s_nop 0
	global_load_lds_dwordx4 v164, s[94:95]
	s_waitcnt vmcnt(8)
	s_barrier
	s_waitcnt lgkmcnt(0)
	s_setprio 1
	v_mfma_f32_16x16x32_bf16 v[62:65], v[130:133], v[208:211], v[62:65]
	ds_read_b128 v[146:149], v241
	v_mfma_f32_16x16x32_bf16 v[58:61], v[138:141], v[208:211], v[58:61]
	v_mfma_f32_16x16x32_bf16 v[54:57], v[130:133], v[216:219], v[54:57]
	ds_read_b128 v[150:153], v241 offset:1024
	v_mfma_f32_16x16x32_bf16 v[50:53], v[138:141], v[216:219], v[50:53]
	v_mfma_f32_16x16x32_bf16 v[42:45], v[130:133], v[224:227], v[42:45]
	ds_read_b128 v[154:157], v241 offset:2048
	v_mfma_f32_16x16x32_bf16 v[34:37], v[138:141], v[224:227], v[34:37]
	v_mfma_f32_16x16x32_bf16 v[26:29], v[130:133], v[232:235], v[26:29]
	ds_read_b128 v[158:161], v241 offset:3072
	v_mfma_f32_16x16x32_bf16 v[18:21], v[138:141], v[232:235], v[18:21]
	v_mfma_f32_16x16x32_bf16 v[62:65], v[134:137], v[212:215], v[62:65]
	ds_read_b128 v[176:179], v241 offset:4096
	v_mfma_f32_16x16x32_bf16 v[58:61], v[142:145], v[212:215], v[58:61]
	v_mfma_f32_16x16x32_bf16 v[54:57], v[134:137], v[220:223], v[54:57]
	ds_read_b128 v[180:183], v241 offset:5120
	v_mfma_f32_16x16x32_bf16 v[50:53], v[142:145], v[220:223], v[50:53]
	v_mfma_f32_16x16x32_bf16 v[42:45], v[134:137], v[228:231], v[42:45]
	ds_read_b128 v[184:187], v241 offset:6144
	v_mfma_f32_16x16x32_bf16 v[34:37], v[142:145], v[228:231], v[34:37]
	v_mfma_f32_16x16x32_bf16 v[26:29], v[134:137], v[246:249], v[26:29]
	ds_read_b128 v[188:191], v241 offset:7168
	v_mfma_f32_16x16x32_bf16 v[18:21], v[142:145], v[246:249], v[18:21]
	s_add_u32 s50, s50, 0x80080
	s_addc_u32 s51, s51, 0
	s_add_i32 s52, s52, s56
	s_mov_b32 m0, s52
	s_nop 0
	global_load_lds_dwordx4 v162, s[50:51]
	s_add_i32 m0, s52, 0x2000
	s_nop 0
	global_load_lds_dwordx4 v164, s[50:51]
	v_mfma_f32_16x16x32_bf16 v[46:49], v[192:195], v[208:211], v[46:49]
	v_mfma_f32_16x16x32_bf16 v[38:41], v[200:203], v[208:211], v[38:41]
	v_mfma_f32_16x16x32_bf16 v[30:33], v[192:195], v[216:219], v[30:33]
	v_mfma_f32_16x16x32_bf16 v[22:25], v[200:203], v[216:219], v[22:25]
	ds_read_b128 v[130:133], v240
	v_mfma_f32_16x16x32_bf16 v[14:17], v[192:195], v[224:227], v[14:17]
	v_mfma_f32_16x16x32_bf16 v[10:13], v[200:203], v[224:227], v[10:13]
	ds_read_b128 v[134:137], v240 offset:1024
	v_mfma_f32_16x16x32_bf16 v[6:9], v[192:195], v[232:235], v[6:9]
	v_mfma_f32_16x16x32_bf16 v[2:5], v[200:203], v[232:235], v[2:5]
	ds_read_b128 v[138:141], v240 offset:2048
	v_mfma_f32_16x16x32_bf16 v[46:49], v[196:199], v[212:215], v[46:49]
	v_mfma_f32_16x16x32_bf16 v[38:41], v[204:207], v[212:215], v[38:41]
	ds_read_b128 v[142:145], v240 offset:3072
	v_mfma_f32_16x16x32_bf16 v[30:33], v[196:199], v[220:223], v[30:33]
	v_mfma_f32_16x16x32_bf16 v[22:25], v[204:207], v[220:223], v[22:25]
	v_mfma_f32_16x16x32_bf16 v[14:17], v[196:199], v[228:231], v[14:17]
	v_mfma_f32_16x16x32_bf16 v[10:13], v[204:207], v[228:231], v[10:13]
	v_mfma_f32_16x16x32_bf16 v[6:9], v[196:199], v[246:249], v[6:9]
	v_mfma_f32_16x16x32_bf16 v[2:5], v[204:207], v[246:249], v[2:5]
	s_waitcnt lgkmcnt(0)
	s_setprio 0
	s_add_i32 s80, s80, 2
	s_add_u32 s48, s48, 0x100
	s_addc_u32 s49, s49, 0
	s_add_u32 s74, s74, 0x100
	s_addc_u32 s75, s75, 0
	s_cmp_gt_u32 s80, s87
	s_barrier
	s_cbranch_scc0 .LBB0_1098
